# operand-prep loop: token-row loads of the in-projection output also non-temporal (on top of the non-temporal P0 input loads)
# speedup vs baseline: 1.0039x; 1.0039x over previous
; #define LAS __attribute__((address_space(3)))
; __device__ __forceinline__ f32x4 bf4(v2u u) { return (f32x4){bflo(u.x), bfhi(u.x), bflo(u.y), bfhi(u.y)}; }
; __device__ __forceinline__ void rw_chunk_prep(const Args& a, int head, int tc0, const LAS bf16* TDr, const LAS bf16* DAr, LAS unsigned char* lw_, int lane) {
;     ...
;     const bf16* ZA = (const bf16*)(ws + WS_ZA);
;     const int j = lane & 15, rg = lane >> 4, kg = rg, cbase = head * 64 + 4 * j;
;     const bf16* W2t = (const bf16*)(ws + WS_W2T); const bf16* A2t = (const bf16*)(ws + WS_A2T);
;     f32x4 accw[4], acca[4];
;     {   bf16x8 atd[2], ada[2];
; #pragma unroll
;         for (int kk = 0; kk < 2; ++kk) { atd[kk] = *(const LAS bf16x8*)(TDr + j * 64 + kk * 32 + kg * 8); ada[kk] = *(const LAS bf16x8*)(DAr + j * 64 + kk * 32 + kg * 8); }
; #pragma unroll
;         for (int cb = 0; cb < 4; ++cb) { accw[cb] = (f32x4){0.f, 0.f, 0.f, 0.f}; acca[cb] = (f32x4){0.f, 0.f, 0.f, 0.f};
; #pragma unroll
;             for (int kk = 0; kk < 2; ++kk) { const bf16x8 bw = *(const bf16x8*)(W2t + (size_t)(cbase + cb) * 64 + kk * 32 + kg * 8), ba = *(const bf16x8*)(A2t + (size_t)(cbase + cb) * 64 + kk * 32 + kg * 8);
;                 accw[cb] = MFMA32(atd[kk], bw, accw[cb]); acca[cb] = MFMA32(ada[kk], ba, acca[cb]); } }
;     }
;     const f32x4 w0 = ld4(a.in[9] + cbase), a0 = ld4(a.in[11] + cbase), kkw = ld4(a.in[13] + cbase), kaw = ld4(a.in[14] + cbase), rkw = ld4(a.in[15] + cbase);
;     const f32x4 mur = ld4(a.in[4] + cbase), muk = ld4(a.in[5] + cbase), muv = ld4(a.in[6] + cbase);
;     float* RK = (float*)(ws + WS_RK);
;     f32x4 rr[4], km[4], av[4], bv[4], lw[4], vv[4];
;     {   const int tt0 = tc0 + 4 * rg; const f32x4 zero = {0.f, 0.f, 0.f, 0.f};
;         f32x4 pr = tt0 > 0 ? bf4(*(const v2u*)(ZA + (size_t)(tt0 - 1) * 3072 + cbase)) : zero;
;         f32x4 pk = tt0 > 0 ? bf4(*(const v2u*)(ZA + (size_t)(tt0 - 1) * 3072 + 1024 + cbase)) : zero;
;         f32x4 pv = tt0 > 0 ? bf4(*(const v2u*)(ZA + (size_t)(tt0 - 1) * 3072 + 2048 + cbase)) : zero;
; #pragma unroll
;         for (int i = 0; i < 4; ++i) {
;             const int tt = tt0 + i;
;             const f32x4 zr = bf4(*(const v2u*)(ZA + (size_t)tt * 3072 + cbase)), zk = bf4(*(const v2u*)(ZA + (size_t)tt * 3072 + 1024 + cbase)), zv = bf4(*(const v2u*)(ZA + (size_t)tt * 3072 + 2048 + cbase));
.LBB0_329:
	s_lshr_b32 s0, s59, 1
	s_add_i32 s0, s0, s34
	s_and_b32 s2, s58, 16
	v_lshl_add_u32 v4, s2, 7, v155
	v_lshl_or_b32 v66, s0, 6, v154
	ds_read_b128 v[0:3], v4
	ds_read_b128 v[16:19], v4 offset:4096
	ds_read_b128 v[20:23], v4 offset:64
	ds_read_b128 v[36:39], v4 offset:4160
	v_lshlrev_b64 v[4:5], 7, v[66:67]
	v_lshl_add_u64 v[12:13], v[74:75], 0, v[4:5]
	v_lshl_add_u64 v[24:25], v[76:77], 0, v[4:5]
	global_load_dwordx4 v[4:7], v[12:13], off
	global_load_dwordx4 v[8:11], v[24:25], off
	global_load_dwordx4 v[12:15], v[12:13], off offset:64
	global_load_dwordx4 v[24:27], v[24:25], off offset:64
	v_or_b32_e32 v214, 1, v66
	v_mov_b32_e32 v215, v67
	v_lshlrev_b64 v[214:215], 7, v[214:215]
	v_lshl_add_u64 v[218:219], v[76:77], 0, v[214:215]
	v_lshl_add_u64 v[214:215], v[74:75], 0, v[214:215]
	global_load_dwordx4 v[206:209], v[214:215], off
	global_load_dwordx4 v[210:213], v[218:219], off
	global_load_dwordx4 v[214:217], v[214:215], off offset:64
	global_load_dwordx4 v[218:221], v[218:219], off offset:64
	v_or_b32_e32 v230, 2, v66
	v_mov_b32_e32 v231, v67
	v_lshlrev_b64 v[230:231], 7, v[230:231]
	v_lshl_add_u64 v[234:235], v[76:77], 0, v[230:231]
	v_lshl_add_u64 v[230:231], v[74:75], 0, v[230:231]
	global_load_dwordx4 v[222:225], v[230:231], off
	global_load_dwordx4 v[226:229], v[234:235], off
	global_load_dwordx4 v[230:233], v[230:231], off offset:64
	global_load_dwordx4 v[234:237], v[234:235], off offset:64
	v_or_b32_e32 v246, 3, v66
	v_mov_b32_e32 v247, v67
	v_lshlrev_b64 v[246:247], 7, v[246:247]
	v_lshl_add_u64 v[250:251], v[76:77], 0, v[246:247]
	v_lshl_add_u64 v[246:247], v[74:75], 0, v[246:247]
	global_load_dwordx4 v[238:241], v[246:247], off
	global_load_dwordx4 v[242:245], v[250:251], off
	global_load_dwordx4 v[246:249], v[246:247], off offset:64
	global_load_dwordx4 v[250:253], v[250:251], off offset:64
	s_or_b32 s60, s2, s57
	v_add_u32_e32 v106, s60, v157
	v_cmp_lt_i32_e32 vcc, 0, v106
	v_mov_b32_e32 v186, 0
	v_add_u32_e32 v96, -1, v106
	v_mov_b32_e32 v98, 0
	v_mov_b32_e32 v100, 0
	v_mov_b32_e32 v99, 0
	v_mov_b32_e32 v101, 0
	s_waitcnt vmcnt(15) lgkmcnt(3)
	v_mfma_f32_16x16x32_bf16 v[4:7], v[0:3], v[4:7], 0
	s_waitcnt vmcnt(14) lgkmcnt(2)
	v_mfma_f32_16x16x32_bf16 v[8:11], v[16:19], v[8:11], 0
	s_waitcnt vmcnt(12) lgkmcnt(0)
	v_mfma_f32_16x16x32_bf16 v[24:27], v[36:39], v[24:27], v[8:11]
	v_mfma_f32_16x16x32_bf16 v[4:7], v[20:23], v[12:15], v[4:7]
	s_nop 4
	s_waitcnt vmcnt(11)
	v_mfma_f32_16x16x32_bf16 v[8:11], v[0:3], v[206:209], 0
	s_waitcnt vmcnt(10)
	v_mfma_f32_16x16x32_bf16 v[12:15], v[16:19], v[210:213], 0
	s_waitcnt vmcnt(9)
	v_mfma_f32_16x16x32_bf16 v[8:11], v[20:23], v[214:217], v[8:11]
	s_waitcnt vmcnt(8)
	v_mfma_f32_16x16x32_bf16 v[28:31], v[36:39], v[218:221], v[12:15]
	s_nop 3
	s_waitcnt vmcnt(7)
	v_mfma_f32_16x16x32_bf16 v[12:15], v[0:3], v[222:225], 0
	s_waitcnt vmcnt(6)
	v_mfma_f32_16x16x32_bf16 v[32:35], v[16:19], v[226:229], 0
	s_waitcnt vmcnt(5)
	v_mfma_f32_16x16x32_bf16 v[12:15], v[20:23], v[230:233], v[12:15]
	s_waitcnt vmcnt(4)
	v_mfma_f32_16x16x32_bf16 v[32:35], v[36:39], v[234:237], v[32:35]
	s_waitcnt vmcnt(3)
	v_mfma_f32_16x16x32_bf16 v[0:3], v[0:3], v[238:241], 0
	s_waitcnt vmcnt(2)
	v_mfma_f32_16x16x32_bf16 v[40:43], v[16:19], v[242:245], 0
	s_waitcnt vmcnt(1)
	v_mfma_f32_16x16x32_bf16 v[16:19], v[20:23], v[246:249], v[0:3]
	s_nop 2
	v_lshlrev_b64 v[0:1], 2, v[66:67]
	v_lshl_add_u64 v[2:3], s[38:39], 0, v[0:1]
	global_load_dwordx4 v[20:23], v[2:3], off
	v_lshl_add_u64 v[2:3], s[42:43], 0, v[0:1]
	global_load_dwordx4 v[60:63], v[2:3], off
	v_lshl_add_u64 v[2:3], s[46:47], 0, v[0:1]
	s_waitcnt vmcnt(2)
	v_mfma_f32_16x16x32_bf16 v[56:59], v[36:39], v[250:253], v[40:43]
	global_load_dwordx4 v[36:39], v[2:3], off
	v_lshl_add_u64 v[2:3], s[48:49], 0, v[0:1]
	global_load_dwordx4 v[52:55], v[2:3], off
	v_lshl_add_u64 v[2:3], s[50:51], 0, v[0:1]
	global_load_dwordx4 v[40:43], v[2:3], off
	v_lshl_add_u64 v[2:3], s[76:77], 0, v[0:1]
	global_load_dwordx4 v[44:47], v[2:3], off
	v_lshl_add_u64 v[2:3], s[78:79], 0, v[0:1]
	v_lshl_add_u64 v[0:1], s[80:81], 0, v[0:1]
	global_load_dwordx4 v[48:51], v[2:3], off
	v_lshlrev_b32_e32 v66, 1, v66
	global_load_dwordx4 v[0:3], v[0:1], off
	v_mov_b32_e32 v102, 0
	v_mov_b32_e32 v103, 0
	v_mov_b32_e32 v104, 0
	v_mov_b32_e32 v105, 0
	v_mov_b32_e32 v188, 0
	v_mov_b32_e32 v187, 0
	v_mov_b32_e32 v189, 0
	s_and_saveexec_b64 s[2:3], vcc
	v_mov_b64_e32 v[108:109], s[72:73]
	v_mad_u64_u32 v[108:109], s[26:27], v96, s44, v[108:109]
	v_lshl_add_u64 v[108:109], v[108:109], 0, v[66:67]
	global_load_dwordx2 v[100:101], v[108:109], off nt
	global_load_dwordx2 v[104:105], v[108:109], off offset:2048 nt
	v_add_co_u32_e32 v108, vcc, 0x1000, v108
	s_nop 1
	v_addc_co_u32_e32 v109, vcc, 0, v109, vcc
	global_load_dwordx2 v[96:97], v[108:109], off nt
	s_waitcnt vmcnt(0)
	v_lshlrev_b32_e32 v98, 16, v100
	v_and_b32_e32 v100, 0xffff0000, v100
	v_lshlrev_b32_e32 v99, 16, v101
	v_and_b32_e32 v101, 0xffff0000, v101
	v_lshlrev_b32_e32 v102, 16, v104
	v_and_b32_e32 v103, 0xffff0000, v104
	v_lshlrev_b32_e32 v104, 16, v105
	v_and_b32_e32 v105, 0xffff0000, v105
	v_lshlrev_b32_e32 v186, 16, v96
	v_and_b32_e32 v188, 0xffff0000, v96
	v_lshlrev_b32_e32 v187, 16, v97
	v_and_b32_e32 v189, 0xffff0000, v97
; __device__ __forceinline__ f32x4 bf4(v2u u) { return (f32x4){bflo(u.x), bfhi(u.x), bflo(u.y), bfhi(u.y)}; }
; __device__ __forceinline__ void rw_chunk_prep(const Args& a, int head, int tc0, const LAS bf16* TDr, const LAS bf16* DAr, LAS unsigned char* lw_, int lane) {
;     ...
;     {   const int tt0 = tc0 + 4 * rg; const f32x4 zero = {0.f, 0.f, 0.f, 0.f};
;         f32x4 pr = tt0 > 0 ? bf4(*(const v2u*)(ZA + (size_t)(tt0 - 1) * 3072 + cbase)) : zero;
;         f32x4 pk = tt0 > 0 ? bf4(*(const v2u*)(ZA + (size_t)(tt0 - 1) * 3072 + 1024 + cbase)) : zero;
;         f32x4 pv = tt0 > 0 ? bf4(*(const v2u*)(ZA + (size_t)(tt0 - 1) * 3072 + 2048 + cbase)) : zero;
; #pragma unroll
;         for (int i = 0; i < 4; ++i) {
;             const int tt = tt0 + i;
;             const f32x4 zr = bf4(*(const v2u*)(ZA + (size_t)tt * 3072 + cbase)), zk = bf4(*(const v2u*)(ZA + (size_t)tt * 3072 + 1024 + cbase)), zv = bf4(*(const v2u*)(ZA + (size_t)tt * 3072 + 2048 + cbase));
;             const f32x4 r = zr + (pr - zr) * mur, k = zk + (pk - zk) * muk, v = zv + (pv - zv) * muv;
;             pr = zr; pk = zk; pv = zv;
;             f32x4 lwv, alr;
; #pragma unroll
;             for (int cb = 0; cb < 4; ++cb) { const float x = -(w0[cb] + accw[cb][i]); const float sp = fmaxf(x, 0.f) + __logf(1.f + __expf(-fabsf(x))); lwv[cb] = -__expf(-sp - 0.5f); alr[cb] = __builtin_amdgcn_rcpf(1.f + __expf(-(a0[cb] + acca[cb][i]))); }
;             const f32x4 kkr = k * kkw, kmod = k * (1.f + (alr - 1.f) * kaw);
;             float ssq = (kkr.x * kkr.x + kkr.y * kkr.y) + (kkr.z * kkr.z + kkr.w * kkr.w);
;             const f32x4 rkk = r * kmod * rkw; float rkp = (rkk.x + rkk.y) + (rkk.z + rkk.w);
;             ssq = row16_sum(ssq); rkp = row16_sum(rkp);
;             const float inv = __builtin_amdgcn_rsqf(fmaxf(ssq, 1e-24f));
;             const f32x4 kk = kkr * inv;
;             rr[i] = r; km[i] = kmod; av[i] = -kk; bv[i] = kk * alr; lw[i] = lwv; vv[i] = v;
;             if (j == 0) RK[(size_t)tt * 16 + head] = rkp;
.LBB0_335:
	s_or_b64 exec, exec, s[2:3]
	v_mov_b64_e32 v[96:97], s[72:73]
	v_mad_i64_i32 v[96:97], s[2:3], v106, s44, v[96:97]
	v_lshl_add_u64 v[96:97], v[96:97], 0, v[66:67]
	global_load_dwordx2 v[108:109], v[96:97], off nt
	global_load_dwordx2 v[110:111], v[96:97], off offset:2048 nt
	v_add_co_u32_e32 v96, vcc, s45, v96
	s_waitcnt vmcnt(8)
	v_add_f32_e32 v107, v24, v60
	v_addc_co_u32_e32 v97, vcc, 0, v97, vcc
	global_load_dwordx2 v[96:97], v[96:97], off nt
	v_mov_b32_e32 v230, s45
	v_mov_b32_e32 v231, 0
	v_or_b32_e32 v224, 1, v106
	v_mov_b64_e32 v[226:227], s[72:73]
	v_mad_i64_i32 v[226:227], s[2:3], v224, s44, v[226:227]
	v_lshl_add_u64 v[226:227], v[226:227], 0, v[66:67]
	v_lshl_add_u64 v[228:229], v[226:227], 0, v[230:231]
	global_load_dwordx2 v[206:207], v[226:227], off nt
	global_load_dwordx2 v[208:209], v[226:227], off offset:2048 nt
	global_load_dwordx2 v[210:211], v[228:229], off nt
	v_or_b32_e32 v224, 2, v106
	v_mov_b64_e32 v[232:233], s[72:73]
	v_mad_i64_i32 v[232:233], s[2:3], v224, s44, v[232:233]
	v_lshl_add_u64 v[232:233], v[232:233], 0, v[66:67]
	v_lshl_add_u64 v[234:235], v[232:233], 0, v[230:231]
	global_load_dwordx2 v[212:213], v[232:233], off nt
	global_load_dwordx2 v[214:215], v[232:233], off offset:2048 nt
	global_load_dwordx2 v[216:217], v[234:235], off nt
	v_or_b32_e32 v224, 3, v106
	v_mov_b64_e32 v[238:239], s[72:73]
	v_mad_i64_i32 v[238:239], s[2:3], v224, s44, v[238:239]
	v_lshl_add_u64 v[238:239], v[238:239], 0, v[66:67]
	v_lshl_add_u64 v[240:241], v[238:239], 0, v[230:231]
	global_load_dwordx2 v[218:219], v[238:239], off nt
	global_load_dwordx2 v[220:221], v[238:239], off offset:2048 nt
	global_load_dwordx2 v[222:223], v[240:241], off nt
	v_add_f32_e32 v28, v28, v61
	v_add_f32_e32 v32, v32, v62
	v_add_f32_e32 v56, v56, v63
	v_mul_f32_e32 v107, 0xbfb8aa3b, v107
	v_mul_f32_e32 v28, 0xbfb8aa3b, v28
	v_mul_f32_e32 v32, 0xbfb8aa3b, v32
	v_mul_f32_e32 v56, 0xbfb8aa3b, v56
	v_exp_f32_e32 v107, v107
	v_exp_f32_e32 v28, v28
	v_exp_f32_e32 v32, v32
	v_exp_f32_e32 v56, v56
	v_add_f32_e32 v107, 1.0, v107
	v_add_f32_e32 v28, 1.0, v28
	v_add_f32_e32 v32, 1.0, v32
	v_add_f32_e32 v56, 1.0, v56
	v_rcp_f32_e32 v112, v107
	v_rcp_f32_e32 v114, v32
	v_rcp_f32_e32 v115, v56
	v_rcp_f32_e32 v113, v28
	s_lshl_b64 s[2:3], s[0:1], 2
	v_mov_b32_e32 v190, v67
	v_pk_add_f32 v[116:117], v[114:115], -1.0 op_sel_hi:[1,0]
	v_pk_add_f32 v[118:119], v[112:113], -1.0 op_sel_hi:[1,0]
	s_waitcnt vmcnt(16)
	v_pk_fma_f32 v[130:131], v[54:55], v[116:117], 1.0 op_sel_hi:[1,1,0]
	v_pk_fma_f32 v[128:129], v[52:53], v[118:119], 1.0 op_sel_hi:[1,1,0]
	v_mov_b32_e32 v24, v67
	s_add_u32 s26, s35, s2
	s_addc_u32 s27, s36, s3
	s_waitcnt vmcnt(11)
	v_lshlrev_b32_e32 v122, 16, v108
	v_and_b32_e32 v123, 0xffff0000, v108
	v_lshlrev_b32_e32 v124, 16, v109
	s_waitcnt vmcnt(10)
	v_lshlrev_b32_e32 v120, 16, v110
	v_and_b32_e32 v121, 0xffff0000, v110
	v_lshlrev_b32_e32 v126, 16, v111
	v_and_b32_e32 v127, 0xffff0000, v111
	v_and_b32_e32 v125, 0xffff0000, v109
	v_sub_f32_e32 v109, v100, v123
	v_sub_f32_e32 v108, v98, v122
	v_sub_f32_e32 v100, v99, v124
	v_sub_f32_e32 v99, v105, v127
	v_sub_f32_e32 v98, v104, v126
	v_sub_f32_e32 v103, v103, v121
	v_sub_f32_e32 v102, v102, v120
	v_sub_f32_e32 v101, v101, v125
	v_pk_fma_f32 v[102:103], v[48:49], v[102:103], v[120:121]
	v_pk_fma_f32 v[98:99], v[50:51], v[98:99], v[126:127]
	v_pk_fma_f32 v[110:111], v[46:47], v[100:101], v[124:125]
	v_pk_fma_f32 v[108:109], v[44:45], v[108:109], v[122:123]
	v_pk_mul_f32 v[118:119], v[38:39], v[98:99]
	v_pk_mul_f32 v[116:117], v[36:37], v[102:103]
	v_pk_mul_f32 v[100:101], v[130:131], v[98:99]
	v_pk_mul_f32 v[102:103], v[128:129], v[102:103]
	v_pk_mul_f32 v[98:99], v[118:119], v[118:119]
	v_pk_mul_f32 v[104:105], v[116:117], v[116:117]
	v_pk_mul_f32 v[128:129], v[108:109], v[102:103]
	v_pk_mul_f32 v[130:131], v[110:111], v[100:101]
	v_pk_mov_b32 v[132:133], v[104:105], v[98:99] op_sel:[1,0]
	v_mov_b32_e32 v105, v99
	v_pk_mul_f32 v[98:99], v[42:43], v[130:131]
	v_pk_mul_f32 v[128:129], v[40:41], v[128:129]
	v_pk_add_f32 v[104:105], v[132:133], v[104:105]
	v_add_f32_e32 v28, v128, v129
	v_add_f32_e32 v32, v98, v99
	v_add_f32_e32 v56, v104, v105
	v_add_f32_e32 v28, v28, v32
	s_nop 0
	v_add_f32_dpp v32, v56, v56 quad_perm:[1,0,3,2] row_mask:0xf bank_mask:0xf bound_ctrl:1
	v_add_f32_dpp v28, v28, v28 quad_perm:[1,0,3,2] row_mask:0xf bank_mask:0xf bound_ctrl:1
	s_nop 0
	v_add_f32_dpp v32, v32, v32 quad_perm:[2,3,0,1] row_mask:0xf bank_mask:0xf bound_ctrl:1
	v_add_f32_dpp v28, v28, v28 quad_perm:[2,3,0,1] row_mask:0xf bank_mask:0xf bound_ctrl:1
	s_nop 0
	v_add_f32_dpp v191, v32, v32 row_half_mirror row_mask:0xf bank_mask:0xf bound_ctrl:1
	v_add_f32_dpp v28, v28, v28 row_half_mirror row_mask:0xf bank_mask:0xf bound_ctrl:1
	s_nop 0
	v_mov_b32_dpp v190, v191 row_mirror row_mask:0xf bank_mask:0xf
	v_mov_b32_dpp v24, v28 row_mirror row_mask:0xf bank_mask:0xf
	s_and_saveexec_b64 s[2:3], s[24:25]
	s_cbranch_execz .LBB0_337
	v_ashrrev_i32_e32 v107, 31, v106
	v_lshlrev_b64 v[98:99], 6, v[106:107]
	v_lshl_add_u64 v[98:99], s[26:27], 0, v[98:99]
	v_add_f32_e32 v24, v28, v24
	global_store_dword v[98:99], v24, off
